# opt26b: opt26 with the whole instruction stream shifted by 8 bytes (two s_nop at entry) - placement sensitivity check of the opt26 result
# speedup vs baseline: 1.0049x; 1.0040x over previous
; __global__ void __launch_bounds__(512, 2) fwd_megakernel(Args a) {
;     ...
;     const int tid = threadIdx.x, lane = tid & 63, wave = __builtin_amdgcn_readfirstlane(tid >> 6);
;     const int G = gridDim.x, bid = blockIdx.x;
;     const int vcu = (G % 8 == 0) ? (bid % 8) * (G / 8) + bid / 8 : bid;
_Z14fwd_megakernel4Args:
	s_nop 0
	s_nop 0
	s_load_dwordx4 s[48:51], s[0:1], 0xa0
	s_load_dwordx8 s[84:91], s[0:1], 0x80
	s_add_u32 s8, s0, 0xa8
	s_addc_u32 s9, s1, 0
	v_and_b32_e32 v246, 0x3ff, v0
	s_waitcnt lgkmcnt(0)
	s_and_b32 s4, s50, 7
	s_cmp_eq_u32 s4, 0
	v_readfirstlane_b32 s3, v246
	s_cselect_b64 s[46:47], -1, 0
	s_cmp_lg_u32 s4, 0
	v_writelane_b32 v254, s2, 0
	s_cbranch_scc1 .LBB0_2
	s_ashr_i32 s5, s2, 31
	s_lshr_b32 s5, s5, 29
	s_add_i32 s5, s2, s5
	s_ashr_i32 s6, s5, 3
	s_and_b32 s5, s5, -8
	s_ashr_i32 s4, s50, 3
	s_sub_i32 s5, s2, s5
	s_mul_i32 s4, s4, s5
	s_add_i32 s4, s4, s6
	v_writelane_b32 v254, s4, 0
